# v17 + grid barrier: the L1 invalidate is issued right after the arrival atomic and the atomic result is awaited with a counted vmcnt(1), so the invalidate overlaps the rest of the barrier
# speedup vs baseline: 1.0266x; 1.0001x over previous
.LBB0_1898:
	s_mov_b64 s[28:29], exec
	v_mbcnt_lo_u32_b32 v1, s28, 0
	v_mbcnt_hi_u32_b32 v1, s29, v1
	v_cmp_eq_u32_e32 vcc, 0, v1
	s_and_saveexec_b64 s[20:21], vcc
	s_cbranch_execz .LBB0_1900
	s_bcnt1_i32_b64 s24, s[28:29]
	v_mov_b32_e32 v3, s24
	v_readlane_b32 s24, v233, 34
	v_readlane_b32 s25, v233, 35
	s_nop 4
	global_atomic_add v3, v33, v3, s[24:25] sc0
	buffer_inv sc1
.LBB0_1900:
	s_or_b64 exec, exec, s[20:21]
	v_cvt_f32_u32_e32 v4, v2
	s_waitcnt vmcnt(1)
	v_readfirstlane_b32 s20, v3
	v_sub_u32_e32 v3, 0, v2
	v_rcp_iflag_f32_e32 v4, v4
	v_add_u32_e32 v5, s20, v1
	v_mul_f32_e32 v4, 0x4f7ffffe, v4
	v_cvt_u32_f32_e32 v4, v4
	v_mul_lo_u32 v1, v3, v4
	v_mul_hi_u32 v1, v4, v1
	v_add_u32_e32 v1, v4, v1
	v_mul_hi_u32 v1, v5, v1
	v_mul_lo_u32 v3, v1, v2
	v_sub_u32_e32 v3, v5, v3
	v_add_u32_e32 v4, 1, v1
	v_cmp_ge_u32_e32 vcc, v3, v2
	s_nop 1
	v_cndmask_b32_e32 v1, v1, v4, vcc
	v_sub_u32_e32 v4, v3, v2
	v_cndmask_b32_e32 v3, v3, v4, vcc
	v_add_u32_e32 v4, 1, v1
	v_cmp_ge_u32_e32 vcc, v3, v2
	v_add_u32_e32 v3, 1, v5
	s_nop 0
	v_cndmask_b32_e32 v1, v1, v4, vcc
	v_mul_lo_u32 v4, v2, v1
	v_add_u32_e32 v2, v4, v2
	v_cmp_ne_u32_e32 vcc, v3, v2
	s_and_saveexec_b64 s[20:21], vcc
	s_xor_b64 s[20:21], exec, s[20:21]
	s_cbranch_execz .LBB0_1914
	v_readlane_b32 s24, v233, 40
	v_readlane_b32 s25, v233, 41
	s_waitcnt lgkmcnt(0)
	s_nop 3
	global_load_dword v0, v33, s[24:25] sc1
	s_waitcnt vmcnt(0)
	v_cmp_eq_u32_e32 vcc, v0, v1
	s_and_saveexec_b64 s[28:29], vcc
	s_cbranch_execz .LBB0_1913
	s_mov_b32 s24, 1
	s_mov_b64 s[36:37], 0
	s_branch .LBB0_1904
